# acquire invalidate hoisted: wave 1 issues it when it reaches the barrier code (before the store drain), waited for before the closing workgroup barrier; thread 0 issues none
# baseline (speedup 1.0000x reference)
; __device__ __forceinline__ void xcd_barrier(const XcdBarrier& b) {
;     asm volatile("s_waitcnt vmcnt(0)" ::: "memory");
;     __syncthreads();
.LBB0_135:
	s_getreg_b32 s3, hwreg(HW_REG_XCC_ID, 0, 4)
	v_readfirstlane_b32 s4, v208
	s_nop 3
	s_lshr_b32 s4, s4, 6
	s_cmp_lg_u32 s4, 1
	s_cbranch_scc1 .Lw1_p
	buffer_inv sc1
	s_waitcnt vmcnt(1)
	s_branch .Lw1d_p

; __device__ __forceinline__ unsigned xb_ld(unsigned* p)              { return __hip_atomic_load(p, __ATOMIC_RELAXED, __HIP_MEMORY_SCOPE_AGENT); }
; __device__ __forceinline__ void xcd_barrier_complete(unsigned* bar, unsigned x, unsigned& nloc, unsigned& nx) {
;     const unsigned G = gridDim.x * gridDim.y * gridDim.z;
;     unsigned sum, cnt, mine, sp = 0u;
;     for (;;) {
;         sum = 0u; cnt = 0u; mine = 0u;
; #pragma unroll
;         for (unsigned j = 0; j < 16; ++j) { const unsigned c = xb_ld(&bar[XB_XCNT(j)]); sum += c; cnt += (c > 0u) ? 1u : 0u; mine = (j == x) ? c : mine; }
; __device__ __forceinline__ void xcd_barrier(const XcdBarrier& b) {
;     ...
;     if (threadIdx.x == 0) {
;         unsigned* bar = b.bar;
;         __builtin_amdgcn_s_waitcnt(0);
;         unsigned nloc = b.st[0], nx = b.st[1];
;         if (nloc == 0u) { xcd_barrier_complete(bar, b.x, nloc, nx); b.st[0] = nloc; b.st[1] = nx; }
.Lw1d_p:
	s_barrier
	s_mov_b64 s[0:1], exec
	v_readlane_b32 s4, v253, 2
	v_readlane_b32 s5, v253, 3
	s_and_b64 s[4:5], s[0:1], s[4:5]
	s_mov_b64 exec, s[4:5]
	s_cbranch_execz .LBB0_187
	s_add_i32 s4, 0, 0x20020
	v_mov_b32_e32 v0, s4
	s_waitcnt vmcnt(0) expcnt(0) lgkmcnt(0)
	ds_read_b32 v2, v0
	s_add_i32 s4, 0, 0x20024
	v_mov_b32_e32 v0, s4
	ds_read_b32 v0, v0
	s_and_b32 s3, s3, 15
	s_waitcnt lgkmcnt(1)
	v_cmp_ne_u32_e32 vcc, 0, v2
	s_cbranch_vccnz .LBB0_151
	s_add_u32 s4, s78, 0x1700200
	s_addc_u32 s5, s79, 0
	s_add_u32 s6, s78, 0x1700400
	s_addc_u32 s7, s79, 0
	s_add_u32 s8, s78, 0x1700500
	s_addc_u32 s9, s79, 0
	s_add_u32 s10, s78, 0x1700600
	s_addc_u32 s11, s79, 0
	s_add_u32 s12, s78, 0x1700700
	s_addc_u32 s13, s79, 0
	s_add_u32 s14, s78, 0x1700800
	s_addc_u32 s15, s79, 0
	s_add_u32 s16, s78, 0x1700900
	s_addc_u32 s17, s79, 0
	s_add_u32 s18, s78, 0x1700a00
	s_addc_u32 s19, s79, 0
	s_add_u32 s20, s78, 0x1700b00
	s_addc_u32 s21, s79, 0
	s_add_u32 s22, s78, 0x1700c00
	s_addc_u32 s23, s79, 0
	s_add_u32 s24, s78, 0x1700d00
	s_addc_u32 s25, s79, 0
	s_add_u32 s26, s78, 0x1700e00
	s_addc_u32 s27, s79, 0
	s_add_u32 s28, s78, 0x1700f00
	s_addc_u32 s29, s79, 0
	s_add_u32 s30, s78, 0x1701000
	s_addc_u32 s31, s79, 0
	s_add_u32 s34, s78, 0x1701100
	s_addc_u32 s35, s79, 0
	s_add_u32 s36, s78, 0x1701200
	s_addc_u32 s37, s79, 0
	s_mul_i32 s33, s43, s2
	s_add_u32 s38, s78, 0x1701300
	s_mul_i32 s33, s33, s42
	s_addc_u32 s39, s79, 0
	s_mov_b32 s50, 1
	v_mov_b32_e32 v16, 0
	s_branch .LBB0_139

; #define LAS __attribute__((address_space(3)))
; #define GRID_BARRIER() do { XcdBarrier xb_; xb_.bar = (unsigned*)(a.ws + WS_BAR); xb_.x = xb_xcc_id(); xb_.st = (volatile LAS unsigned*)(lds + 131072) + 8; xcd_barrier(xb_); } while (0)
; #define FRESH_TID() int tid = threadIdx.x; asm volatile("" : "+v"(tid)); const int lane = tid & 63, wave = __builtin_amdgcn_readfirstlane(tid >> 6)
; __device__ __forceinline__ void xcd_barrier(const XcdBarrier& b) {
;     ...
;     __syncthreads();
; }
; __global__ void __launch_bounds__(512, 2) fwd_megakernel(Args a) {
;     extern __shared__ __attribute__((aligned(16))) unsigned char lds_raw[];
;     LAS unsigned char* lds = (LAS unsigned char*)lds_raw;
;     cg::grid_group grid = cg::this_grid();
;     const int bid = blockIdx.x, G = gridDim.x;
;     if (threadIdx.x < 64) ((LAS unsigned*)(lds + 131072))[threadIdx.x] = 0u;
;     __syncthreads();
;     (void)xcd_barrier_post((unsigned*)(a.ws + WS_BAR), (volatile LAS unsigned*)(lds + 131072) + 8);
;     ...
;     if (a.ws == nullptr) grid.sync();
;     { FRESH_TID(); p0_phase(a, lds, tid, lane, wave, bid, G); }
;     GRID_BARRIER();
; #pragma unroll 1
;     for (int l = 0; l < 2; ++l) {
;         { FRESH_TID(); (void)tid; p_norm(a, l, lane, wave, bid, G); }
;     ...
;         { FRESH_TID(); (void)tid; p_norm(a, l, lane, wave, bid, G); }
;     ...
;         GRID_BARRIER();
;         {
;             pg8::Gemm g{(const bf16_t*)(a.ws + WS_H), (const bf16_t*)(a.ws + WS_WIN) + (size_t)l * PO * D, M, PO, D}; pg8::StaticOrder S; S.init(M, PO, G, bid);
;             pg8::EpiProj E{(bf16_t*)(a.ws + WS_PROJ)};
;             pg8::gemm_phase<pg8::EpiProj, pg8::StaticOrder, true, true>(lds, g, S, E);
.LBB0_187:
	s_waitcnt vmcnt(0)
	s_or_b64 exec, exec, s[0:1]
	s_lshl_b32 s24, s71, 3
	s_lshl_b32 s44, s42, 3
	s_add_u32 s0, s78, 0x1200000
	v_writelane_b32 v253, s0, 36
	s_addc_u32 s0, s79, 0
	s_add_u32 s46, s78, 0x1800000
	s_addc_u32 s47, s79, 0
	s_add_u32 s72, s78, 0x1700200
	s_addc_u32 s73, s79, 0
	s_add_u32 s80, s78, 0x1700400
	s_addc_u32 s81, s79, 0
	s_add_u32 s82, s78, 0x1700500
	s_addc_u32 s83, s79, 0
	s_add_u32 s92, s78, 0x1700600
	s_addc_u32 s93, s79, 0
	s_add_u32 s94, s78, 0x1700700
	s_addc_u32 s95, s79, 0
	s_add_u32 s98, s78, 0x1700800
	s_addc_u32 s99, s79, 0
	s_add_u32 s54, s78, 0x1700900
	s_addc_u32 s55, s79, 0
	s_add_u32 s56, s78, 0x1700a00
	s_addc_u32 s57, s79, 0
	s_add_u32 s60, s78, 0x1700b00
	s_addc_u32 s61, s79, 0
	s_add_u32 s62, s78, 0x1700c00
	s_addc_u32 s63, s79, 0
	v_writelane_b32 v253, s0, 37
	s_add_u32 s0, s78, 0x1700d00
	s_addc_u32 s1, s79, 0
	v_writelane_b32 v253, s0, 38
	v_mov_b32_e32 v173, 0
	v_writelane_b32 v255, s60, 0
	v_writelane_b32 v253, s1, 39
	s_add_u32 s0, s78, 0x1700e00
	s_addc_u32 s1, s79, 0
	v_writelane_b32 v253, s0, 40
	v_writelane_b32 v255, s61, 1
	v_writelane_b32 v255, s62, 2
	v_writelane_b32 v253, s1, 41
	s_add_u32 s0, s78, 0x1700f00
	s_addc_u32 s1, s79, 0
	v_writelane_b32 v253, s0, 42
	v_writelane_b32 v255, s63, 3
	s_mov_b32 s87, 0
	v_writelane_b32 v253, s1, 43
	s_add_u32 s0, s78, 0x1701000
	s_addc_u32 s1, s79, 0
	v_writelane_b32 v253, s0, 44
	v_mov_b32_e32 v209, 0x358637bd
	v_mov_b32_e32 v252, 0x1000
	v_writelane_b32 v253, s1, 45
	s_add_u32 s0, s78, 0x1701100
	s_addc_u32 s1, s79, 0
	v_writelane_b32 v253, s0, 46
	v_mov_b32_e32 v221, 0x2000
	v_mov_b32_e32 v212, 1
	v_writelane_b32 v253, s1, 47
	s_add_u32 s0, s78, 0x1701200
	s_addc_u32 s1, s79, 0
	v_writelane_b32 v253, s0, 48
	v_mov_b64_e32 v[174:175], 0x374
	v_mov_b64_e32 v[176:177], 0x373
	v_writelane_b32 v253, s1, 49
	s_add_u32 s0, s78, 0x1701300
	s_addc_u32 s1, s79, 0
	v_writelane_b32 v253, s0, 50
	v_mov_b32_e32 v222, 0xc60
	v_mov_b32_e32 v223, 0xf149f2ca
	v_writelane_b32 v253, s1, 51
	s_add_u32 s0, s78, 0x1703400
	s_addc_u32 s1, s79, 0
	v_writelane_b32 v253, s0, 52
	v_mov_b32_e32 v224, 0x800
	v_mov_b32_e32 v225, 0xfffffc00
	v_writelane_b32 v253, s1, 53
	s_add_u32 s0, s78, 0x1703500
	s_addc_u32 s1, s79, 0
	s_add_u32 s74, s78, 0x3a00000
	s_addc_u32 s75, s79, 0
	v_writelane_b32 v253, s0, 54
	s_cmpk_lt_i32 s71, 0x374
	v_mov_b32_e32 v226, 0x3c00
	v_writelane_b32 v253, s1, 55
	s_cselect_b64 s[0:1], -1, 0
	v_writelane_b32 v253, s0, 56
	s_ashr_i32 s33, s71, 31
	s_ashr_i32 s91, s42, 31
	v_writelane_b32 v253, s1, 57
	s_lshr_b32 s0, s33, 29
	s_add_i32 s0, s71, s0
	s_ashr_i32 s3, s0, 3
	s_and_b32 s0, s0, -8
	s_sub_i32 s4, s71, s0
	s_mul_i32 s0, s4, 0x6e
	s_add_i32 s5, s0, 4
	s_cmpk_lg_i32 s42, 0x100
	s_cselect_b64 s[6:7], -1, 0
	s_cmpk_lt_i32 s71, 0x74
	s_cselect_b64 s[0:1], -1, 0
	v_writelane_b32 v253, s6, 58
	s_or_b64 s[0:1], s[0:1], s[6:7]
	v_writelane_b32 v255, s33, 4
	v_writelane_b32 v253, s7, 59
	v_writelane_b32 v253, s0, 60
	v_mov_b32_e32 v232, v173
	v_mov_b32_e32 v233, v173
	v_writelane_b32 v253, s1, 61
	s_add_u32 s0, s78, 0x1000000
	s_addc_u32 s1, s79, 0
	v_writelane_b32 v253, s0, 62
	v_mov_b32_e32 v234, v173
	v_mov_b32_e32 v235, v173
	v_writelane_b32 v253, s1, 63
	s_add_u32 s0, s78, 0x680000
	v_readlane_b32 s8, v253, 20
	v_readlane_b32 s9, v253, 21
	v_readlane_b32 s10, v253, 22
	v_readlane_b32 s11, v253, 23
	v_readlane_b32 s12, v253, 24
	v_readlane_b32 s13, v253, 25
	v_readlane_b32 s14, v253, 26
	v_readlane_b32 s15, v253, 27
	v_readlane_b32 s16, v253, 28
	v_readlane_b32 s17, v253, 29
	v_readlane_b32 s18, v253, 30
	v_readlane_b32 s19, v253, 31
	s_addc_u32 s1, s79, 0
	v_readlane_b32 s20, v253, 32
	v_readlane_b32 s21, v253, 33
	v_readlane_b32 s22, v253, 34
	v_readlane_b32 s23, v253, 35
	s_mov_b64 s[8:9], s[12:13]
	v_writelane_b32 v254, s0, 0
	s_mov_b64 s[10:11], s[14:15]
	s_mov_b64 s[12:13], s[16:17]
	s_mov_b64 s[14:15], s[18:19]
	s_mov_b64 s[16:17], s[20:21]
	s_mov_b64 s[18:19], s[22:23]
	v_writelane_b32 v254, s1, 1
	s_add_u32 s0, s18, 0x400000
	s_addc_u32 s1, s19, 0
	v_writelane_b32 v254, s0, 2
	v_mov_b64_e32 v[178:179], 0x100
	v_mov_b64_e32 v[180:181], 0xff
	v_writelane_b32 v254, s1, 3
	s_add_u32 s0, s8, 0xd00000
	s_addc_u32 s1, s9, 0
	v_writelane_b32 v254, s0, 4
	s_mov_b32 s96, 0x800000
	s_movk_i32 s97, 0x1200
	v_writelane_b32 v254, s1, 5
	v_writelane_b32 v254, s24, 6
	s_add_i32 s0, s24, 0xfffffc60
	v_writelane_b32 v254, s0, 7
	s_add_u32 s0, s78, 0x1703800
	v_writelane_b32 v254, s0, 8
	s_addc_u32 s0, s79, 0
	s_bitcmp0_b32 s71, 3
	v_writelane_b32 v254, s0, 9
	s_cselect_b64 s[0:1], -1, 0
	v_writelane_b32 v254, s0, 10
	s_cmpk_lt_i32 s71, 0x100
	s_movk_i32 s84, 0x90
	v_writelane_b32 v254, s1, 11
	s_cselect_b64 s[0:1], -1, 0
	s_add_u32 s50, s76, 0x4408000
	s_addc_u32 s51, s77, 0
	s_add_u32 s40, s76, 0x4488000
	v_writelane_b32 v254, s0, 12
	s_addc_u32 s41, s77, 0
	s_mov_b64 s[26:27], 0x1000
	v_writelane_b32 v254, s1, 13
	s_add_u32 s0, s76, 0x4508000
	v_writelane_b32 v254, s0, 14
	s_addc_u32 s0, s77, 0
	v_writelane_b32 v254, s0, 15
	s_add_u32 s0, s76, 0x4400000
	v_writelane_b32 v254, s0, 16
	s_addc_u32 s0, s77, 0
	v_writelane_b32 v254, s0, 17
	s_add_u32 s0, s76, 0x4608000
	v_writelane_b32 v254, s0, 18
	s_addc_u32 s0, s77, 0
	v_writelane_b32 v254, s0, 19
	s_add_u32 s0, s76, 0x5608000
	v_writelane_b32 v254, s0, 20
	s_addc_u32 s0, s77, 0
	v_writelane_b32 v254, s0, 21
	s_add_u32 s0, s78, 0xe00000
	v_writelane_b32 v254, s0, 22
	s_addc_u32 s0, s79, 0
	s_add_u32 s58, s78, 0xaa00000
	v_writelane_b32 v254, s0, 23
	s_addc_u32 s59, s79, 0
	s_bfe_u32 s85, s71, 0x10003
	s_lshl_b32 s0, s4, 5
	s_add_u32 s6, s76, 0x4000000
	s_addc_u32 s7, s77, 0
	v_writelane_b32 v254, s6, 24
	s_mul_i32 s1, s4, 0x6f
	v_writelane_b32 v255, s85, 5
	v_writelane_b32 v254, s7, 25
	s_add_u32 s6, s78, 0xca00000
	s_addc_u32 s7, s79, 0
	s_cmp_lt_i32 s4, 4
	s_cselect_b32 s1, s1, s5
	s_add_i32 s1, s1, s3
	v_writelane_b32 v254, s6, 26
	s_mul_hi_i32 s5, s1, 0x4ec4ec4f
	s_mov_b64 s[88:89], 0x80
	v_writelane_b32 v254, s7, 27
	s_lshr_b32 s6, s5, 31
	s_ashr_i32 s5, s5, 5
	s_add_i32 s5, s5, s6
	s_mul_i32 s6, s5, 0x68
	s_lshl_b32 s5, s5, 3
	s_sub_i32 s6, s1, s6
	s_sub_i32 s1, 0x44, s5
	s_min_u32 s7, s1, 8
	s_cmp_lt_i32 s4, 0
	s_mul_i32 s4, s4, 33
	s_cselect_b32 s0, s4, s0
	s_add_i32 s0, s0, s3
	s_ashr_i32 s1, s0, 31
	s_lshr_b32 s1, s1, 27
	s_add_i32 s1, s0, s1
	s_and_b32 s3, s1, 0xffe0
	s_sub_i32 s0, s0, s3
	s_bfe_i32 s3, s0, 0x80000
	s_bfe_u32 s3, s3, 0x3000c
	s_add_i32 s3, s0, s3
	s_and_b32 s4, s3, 0xf8
	s_sub_i32 s0, s0, s4
	s_ashr_i32 s1, s1, 5
	s_bfe_i32 s3, s3, 0x80000
	s_lshl_b32 s1, s1, 3
	s_sext_i32_i16 s3, s3
	s_sext_i32_i8 s0, s0
	s_add_i32 s8, s1, s0
	s_ashr_i32 s0, s3, 3
	v_writelane_b32 v254, s0, 28
	s_lshr_b32 s0, s3, 3
	s_bfe_i64 s[0:1], s[0:1], 0x100000
	s_lshl_b64 s[0:1], s[0:1], 19
	v_writelane_b32 v254, s0, 29
	v_cvt_f32_ubyte0_e32 v1, s7
	s_waitcnt lgkmcnt(0)
; #define GRID_BARRIER() do { XcdBarrier xb_; xb_.bar = (unsigned*)(a.ws + WS_BAR); xb_.x = xb_xcc_id(); xb_.st = (volatile LAS unsigned*)(lds + 131072) + 8; xcd_barrier(xb_); } while (0)
; #define FRESH_TID() int tid = threadIdx.x; asm volatile("" : "+v"(tid)); const int lane = tid & 63, wave = __builtin_amdgcn_readfirstlane(tid >> 6)
; __global__ void __launch_bounds__(512, 2) fwd_megakernel(Args a) {
;     ...
; #pragma unroll 1
;     for (int l = 0; l < 2; ++l) {
;         { FRESH_TID(); (void)tid; p_norm(a, l, lane, wave, bid, G); }
;     ...
;         { FRESH_TID(); (void)tid; p_norm(a, l, lane, wave, bid, G); }
;     ...
;         GRID_BARRIER();
;         {
;             pg8::Gemm g{(const bf16_t*)(a.ws + WS_H), (const bf16_t*)(a.ws + WS_WIN) + (size_t)l * PO * D, M, PO, D}; pg8::StaticOrder S; S.init(M, PO, G, bid);
;             pg8::EpiProj E{(bf16_t*)(a.ws + WS_PROJ)};
;             pg8::gemm_phase<pg8::EpiProj, pg8::StaticOrder, true, true>(lds, g, S, E);
	v_cvt_f32_i32_e32 v0, s6
	v_writelane_b32 v254, s1, 30
	s_mov_b32 s0, s8
	v_rcp_iflag_f32_e32 v2, v1
	s_ashr_i32 s9, s8, 31
	v_writelane_b32 v254, s0, 31
	s_mov_b32 s90, 0x3e38aa3b
	v_mul_f32_e32 v2, v0, v2
	v_writelane_b32 v254, s1, 32
	s_lshl_b64 s[0:1], s[8:9], 19
	s_add_u32 s0, s46, s0
	s_addc_u32 s1, s47, s1
	s_add_u32 s8, s0, 0x40000
	v_writelane_b32 v254, s0, 33
	v_trunc_f32_e32 v2, v2
	s_addc_u32 s9, s1, 0
	v_writelane_b32 v254, s1, 34
	s_ashr_i32 s0, s6, 30
	v_fma_f32 v0, -v2, v1, v0
	s_or_b32 s3, s0, 1
	v_cmp_ge_f32_e64 s[0:1], |v0|, v1
	v_cvt_i32_f32_e32 v0, v2
	s_and_b64 s[0:1], s[0:1], exec
	v_writelane_b32 v254, s8, 35
	s_mul_i32 s0, s43, s42
	s_mul_i32 s0, s0, s2
	v_writelane_b32 v254, s9, 36
	v_writelane_b32 v254, s0, 37
	s_cselect_b32 s0, s3, 0
	v_readfirstlane_b32 s1, v0
	s_add_i32 s0, s1, s0
	s_mul_i32 s1, s0, s7
	s_sub_i32 s1, s6, s1
	s_sext_i32_i8 s1, s1
	s_add_i32 s1, s5, s1
	v_writelane_b32 v254, s1, 38
	s_sext_i32_i8 s0, s0
	v_writelane_b32 v254, s0, 39
	s_lshl_b32 s0, s71, 2
	v_writelane_b32 v254, s0, 40
	s_lshl_b32 s0, s42, 2
	v_writelane_b32 v254, s0, 41
	s_lshl_b32 s0, s71, 6
	v_writelane_b32 v254, s0, 42
	s_lshl_b32 s0, s42, 6
	v_writelane_b32 v254, s0, 43
	s_add_i32 s0, 0, 0x20020
	v_writelane_b32 v254, s0, 44
	s_add_i32 s0, 0, 0x20024
	v_writelane_b32 v254, s0, 45
	s_add_i32 s0, 0, 0x20080
	v_writelane_b32 v254, s0, 46
	s_add_i32 s0, 0, 0x4c80
	v_writelane_b32 v254, s0, 47
	v_writelane_b32 v254, s72, 48
	s_ashr_i32 s45, s44, 31
	v_mbcnt_lo_u32_b32 v0, -1, 0
	v_writelane_b32 v254, s73, 49
	v_writelane_b32 v254, s80, 50
	v_mbcnt_hi_u32_b32 v213, -1, v0
	s_lshl_b64 s[12:13], s[44:45], 11
	v_writelane_b32 v254, s81, 51
	v_writelane_b32 v254, s82, 52
	v_and_b32_e32 v0, 64, v213
	v_writelane_b32 v255, s12, 6
	v_writelane_b32 v254, s83, 53
	v_writelane_b32 v254, s92, 54
	v_add_u32_e32 v214, 64, v0
	v_xor_b32_e32 v215, 1, v213
	v_writelane_b32 v254, s93, 55
	v_writelane_b32 v254, s94, 56
	v_xor_b32_e32 v216, 2, v213
	v_xor_b32_e32 v217, 4, v213
	v_writelane_b32 v254, s95, 57
	v_writelane_b32 v254, s98, 58
	v_xor_b32_e32 v218, 8, v213
	v_xor_b32_e32 v219, 16, v213
	v_writelane_b32 v254, s99, 59
	v_writelane_b32 v254, s54, 60
	v_xor_b32_e32 v220, 32, v213
	s_lshl_b32 s43, s42, 4
	v_writelane_b32 v254, s55, 61
	v_writelane_b32 v254, s56, 62
	s_mov_b64 s[4:5], -1
	s_mov_b32 s66, s87
	v_writelane_b32 v254, s57, 63
	v_writelane_b32 v255, s13, 7
	s_barrier
	s_branch .LBB0_191

; __device__ __forceinline__ void xcd_barrier(const XcdBarrier& b) {
;     ...
;     }
;     __syncthreads();
; }
.LBB0_189:
	s_waitcnt vmcnt(0)
	s_or_b64 exec, exec, s[0:1]
	s_mov_b64 s[0:1], 0
	s_waitcnt lgkmcnt(0)
	s_barrier

; __device__ __forceinline__ void xcd_barrier(const XcdBarrier& b) {
;     asm volatile("s_waitcnt vmcnt(0)" ::: "memory");
;     __syncthreads();
.LBB0_207:
	s_getreg_b32 s2, hwreg(HW_REG_XCC_ID, 0, 4)
	v_readfirstlane_b32 s3, v208
	s_nop 3
	s_lshr_b32 s3, s3, 6
	s_cmp_lg_u32 s3, 1
	s_cbranch_scc1 .Lw1_n
	buffer_inv sc1
	s_waitcnt vmcnt(1)
	s_branch .Lw1d_n

; __device__ __forceinline__ unsigned xb_ld(unsigned* p)              { return __hip_atomic_load(p, __ATOMIC_RELAXED, __HIP_MEMORY_SCOPE_AGENT); }
; __device__ __forceinline__ unsigned xb_add(unsigned* p, unsigned v) { return __hip_atomic_fetch_add(p, v, __ATOMIC_RELAXED, __HIP_MEMORY_SCOPE_AGENT); }
; #define XB_SPIN(cond, bar) do { unsigned _sp = 0; while (cond) { __builtin_amdgcn_s_sleep(1); \
;     if ((++_sp & 255u) == 0u) { if (xb_ld(&(bar)[XB_TMO])) break; if (_sp > XB_SPIN_CAP) { atomicAdd(&(bar)[XB_TMO], 1u); break; } } } } while (0)
; __device__ __forceinline__ void xcd_barrier(const XcdBarrier& b) {
;     asm volatile("s_waitcnt vmcnt(0)" ::: "memory");
;     __syncthreads();
;     if (threadIdx.x == 0) {
;         unsigned* bar = b.bar;
;         __builtin_amdgcn_s_waitcnt(0);
;         unsigned nloc = b.st[0], nx = b.st[1];
;         if (nloc == 0u) { xcd_barrier_complete(bar, b.x, nloc, nx); b.st[0] = nloc; b.st[1] = nx; }
;         const unsigned old = xb_add(&bar[XB_XSUB(b.x)], 1u);
;         const unsigned gen = old / nloc;
;         if (old + 1u == (gen + 1u) * nloc) {
;             __builtin_amdgcn_fence(__ATOMIC_RELEASE, "agent");
;             asm volatile("s_waitcnt vmcnt(0)" ::: "memory");
;             const unsigned og = xb_add(&bar[XB_TOP], 1u);
;             const unsigned tg = og / nx;
;             if (og + 1u == (tg + 1u) * nx) xb_add(&bar[XB_TOPGEN], 1u);
;             else XB_SPIN(xb_ld(&bar[XB_TOPGEN]) == tg, bar);
;             __builtin_amdgcn_fence(__ATOMIC_ACQUIRE, "agent");
;             xb_add(&bar[XB_XGEN(b.x)], 1u);
;             asm volatile("s_waitcnt vmcnt(0)" ::: "memory");
.Lw1d_n:
	s_barrier
	s_mov_b64 s[0:1], exec
	v_readlane_b32 s4, v253, 2
	v_readlane_b32 s5, v253, 3
	s_and_b64 s[4:5], s[0:1], s[4:5]
	s_mov_b64 exec, s[4:5]
	s_cbranch_execz .LBB0_259
	v_mov_b32_e32 v0, 0x20020
	s_waitcnt vmcnt(0) lgkmcnt(0)
	ds_read2_b32 v[2:3], v0 offset1:1
	s_and_b32 s3, s2, 15
	s_lshl_b32 s3, s3, 8
	s_add_u32 s6, s78, 0x1701400
	s_addc_u32 s7, s79, 0
	s_add_u32 s6, s6, s3
	s_addc_u32 s7, s7, 0
	s_add_u32 s10, s78, 0x1703c00
	s_addc_u32 s11, s79, 0
	s_lshr_b32 s3, s3, 1
	s_add_u32 s8, s10, s3
	s_addc_u32 s9, s11, 0
	s_waitcnt lgkmcnt(0)
	v_readfirstlane_b32 s30, v2
	v_readfirstlane_b32 s31, v3
	s_nop 3
	s_cmp_eq_u32 s30, 0
	s_cbranch_scc1 .Lxb_slow_n
	s_lshl_b32 s29, s66, 2
	s_add_i32 s29, s29, 1
	global_atomic_add v2, v173, v212, s[6:7] sc0
	s_add_i32 s32, s29, 1
	s_mul_i32 s5, s32, s30
	s_mul_i32 s32, s32, s31
	s_waitcnt vmcnt(0)
	v_readfirstlane_b32 s3, v2
	s_nop 3
	s_add_i32 s3, s3, 1
	s_cmp_lg_u32 s3, s5
	s_cbranch_scc1 .Lxb_local_n
	global_atomic_add v173, v212, s[10:11] offset:0
	global_atomic_add v173, v212, s[10:11] offset:128
	global_atomic_add v173, v212, s[10:11] offset:256
	global_atomic_add v173, v212, s[10:11] offset:384
	global_atomic_add v173, v212, s[10:11] offset:512
	global_atomic_add v173, v212, s[10:11] offset:640
	global_atomic_add v173, v212, s[10:11] offset:768
	global_atomic_add v173, v212, s[10:11] offset:896

; __device__ __forceinline__ void xcd_barrier(const XcdBarrier& b) {
;     ...
;     }
;     __syncthreads();
; }
; __global__ void __launch_bounds__(512, 2) fwd_megakernel(Args a) {
;     ...
;         {
;             pg8::Gemm g{(const bf16_t*)(a.ws + WS_H), (const bf16_t*)(a.ws + WS_WIN) + (size_t)l * PO * D, M, PO, D}; pg8::StaticOrder S; S.init(M, PO, G, bid);
;             pg8::EpiProj E{(bf16_t*)(a.ws + WS_PROJ)};
;             pg8::gemm_phase<pg8::EpiProj, pg8::StaticOrder, true, true>(lds, g, S, E);
.LBB0_259:
	s_waitcnt vmcnt(0)
	s_or_b64 exec, exec, s[0:1]
	v_readlane_b32 s2, v253, 56
	v_readlane_b32 s3, v253, 57
	v_mov_b32_e32 v8, v208
	s_waitcnt lgkmcnt(0)
	v_cndmask_b32_e64 v0, 0, 1, s[2:3]
	s_barrier
	v_cmp_ne_u32_e64 s[0:1], 1, v0
	s_andn2_b64 vcc, exec, s[2:3]
	v_readfirstlane_b32 s8, v8
	s_cbranch_vccnz .LBB0_261
	v_readlane_b32 s2, v254, 39
	s_mov_b32 s18, s2
	v_readlane_b32 s2, v254, 38
	s_mov_b32 s4, s2

; __device__ __forceinline__ unsigned xb_ld(unsigned* p)              { return __hip_atomic_load(p, __ATOMIC_RELAXED, __HIP_MEMORY_SCOPE_AGENT); }
; __device__ __forceinline__ unsigned xb_add(unsigned* p, unsigned v) { return __hip_atomic_fetch_add(p, v, __ATOMIC_RELAXED, __HIP_MEMORY_SCOPE_AGENT); }
; #define XB_SPIN(cond, bar) do { unsigned _sp = 0; while (cond) { __builtin_amdgcn_s_sleep(1); \
;     if ((++_sp & 255u) == 0u) { if (xb_ld(&(bar)[XB_TMO])) break; if (_sp > XB_SPIN_CAP) { atomicAdd(&(bar)[XB_TMO], 1u); break; } } } } while (0)
; __device__ __forceinline__ void xcd_barrier(const XcdBarrier& b) {
;     asm volatile("s_waitcnt vmcnt(0)" ::: "memory");
;     __syncthreads();
;     if (threadIdx.x == 0) {
;         unsigned* bar = b.bar;
;         __builtin_amdgcn_s_waitcnt(0);
;         unsigned nloc = b.st[0], nx = b.st[1];
;         if (nloc == 0u) { xcd_barrier_complete(bar, b.x, nloc, nx); b.st[0] = nloc; b.st[1] = nx; }
;         const unsigned old = xb_add(&bar[XB_XSUB(b.x)], 1u);
;         const unsigned gen = old / nloc;
;         if (old + 1u == (gen + 1u) * nloc) {
;             __builtin_amdgcn_fence(__ATOMIC_RELEASE, "agent");
;             asm volatile("s_waitcnt vmcnt(0)" ::: "memory");
;             const unsigned og = xb_add(&bar[XB_TOP], 1u);
;             const unsigned tg = og / nx;
;             if (og + 1u == (tg + 1u) * nx) xb_add(&bar[XB_TOPGEN], 1u);
;             else XB_SPIN(xb_ld(&bar[XB_TOPGEN]) == tg, bar);
;             __builtin_amdgcn_fence(__ATOMIC_ACQUIRE, "agent");
;             xb_add(&bar[XB_XGEN(b.x)], 1u);
;             asm volatile("s_waitcnt vmcnt(0)" ::: "memory");
.Lw1d_i:
	v_writelane_b32 v255, s0, 13
	s_barrier
	v_writelane_b32 v255, s1, 14
	s_mov_b64 s[0:1], exec
	v_readlane_b32 s4, v253, 2
	v_readlane_b32 s5, v253, 3
	s_and_b64 s[4:5], s[0:1], s[4:5]
	s_mov_b64 exec, s[4:5]
	s_cbranch_execz .LBB0_439
	v_mov_b32_e32 v0, 0x20020
	s_waitcnt vmcnt(0) lgkmcnt(0)
	ds_read2_b32 v[2:3], v0 offset1:1
	s_and_b32 s3, s2, 15
	s_lshl_b32 s3, s3, 8
	s_add_u32 s6, s78, 0x1701400
	s_addc_u32 s7, s79, 0
	s_add_u32 s6, s6, s3
	s_addc_u32 s7, s7, 0
	s_add_u32 s10, s78, 0x1703c00
	s_addc_u32 s11, s79, 0
	s_lshr_b32 s3, s3, 1
	s_add_u32 s8, s10, s3
	s_addc_u32 s9, s11, 0
	s_waitcnt lgkmcnt(0)
	v_readfirstlane_b32 s30, v2
	v_readfirstlane_b32 s31, v3
	s_nop 3
	s_cmp_eq_u32 s30, 0
	s_cbranch_scc1 .Lxb_slow_i
	s_lshl_b32 s29, s66, 2
	s_add_i32 s29, s29, 2
	global_atomic_add v2, v173, v212, s[6:7] sc0
	s_add_i32 s32, s29, 1
	s_mul_i32 s5, s32, s30
	s_mul_i32 s32, s32, s31
	s_waitcnt vmcnt(0)
	v_readfirstlane_b32 s3, v2
	s_nop 3
	s_add_i32 s3, s3, 1
	s_cmp_lg_u32 s3, s5
	s_cbranch_scc1 .Lxb_local_i
	buffer_wbl2 sc1
	s_waitcnt vmcnt(0)
	global_atomic_add v173, v212, s[10:11] offset:0
	global_atomic_add v173, v212, s[10:11] offset:128
	global_atomic_add v173, v212, s[10:11] offset:256
	global_atomic_add v173, v212, s[10:11] offset:384
	global_atomic_add v173, v212, s[10:11] offset:512
	global_atomic_add v173, v212, s[10:11] offset:640
	global_atomic_add v173, v212, s[10:11] offset:768
	global_atomic_add v173, v212, s[10:11] offset:896

; #define LAS __attribute__((address_space(3)))
; __device__ __forceinline__ void p_mixer(const Args& a, int l, LAS unsigned char* lds, int tid, int lane, int wave, int bid, int G) {
;     constexpr int N_AP = NPB * 32 * 2, N_AS = NSB, N_CV = M / 64;
;     unsigned* head = (unsigned*)(a.ws + WS_BAR) + QUEUE_WORD + 64 * l;
;     volatile LAS unsigned* slot = (volatile LAS unsigned*)(lds + 131072 + 128);
;     const bool qfirst = ((bid >> 3) & 1) != 0;
;     bool prompt_done = false, queue_empty = false; int pulled = 0;
; __device__ __forceinline__ void xcd_barrier(const XcdBarrier& b) {
;     ...
;     }
;     __syncthreads();
; }
.LBB0_439:
	s_waitcnt vmcnt(0)
	s_or_b64 exec, exec, s[0:1]
	v_mov_b32_e32 v130, v208
	s_waitcnt lgkmcnt(0)
	s_barrier
	s_lshl_b32 s86, s66, 6
	v_readfirstlane_b32 s2, v130
	s_ashr_i32 s6, s2, 6
	s_lshl_b64 s[0:1], s[86:87], 2
	v_readlane_b32 s3, v254, 8
	s_add_u32 s4, s3, s0
	v_readlane_b32 s3, v254, 9
	s_addc_u32 s5, s3, s1
	v_writelane_b32 v255, s4, 15
	s_ashr_i32 s45, s2, 7
	s_lshl_b32 s2, s6, 1
	v_writelane_b32 v255, s5, 16
	s_and_b32 s2, s2, 2
	s_lshl_b32 s4, s6, 12
	s_add_i32 s7, s4, 0
	s_mul_i32 s4, s2, 0x1200
	s_lshl_b32 s33, s2, 5
	s_add_i32 s85, s4, 0
	s_mul_i32 s4, s2, 0xfffff600
	s_sub_i32 s61, 4, s2
	s_xor_b32 s83, s2, 3
	s_lshl_b32 s2, s6, 3
	s_lshl_b32 s10, s6, 8
	s_addk_i32 s2, 0xe000
	s_add_i32 s8, s10, 0
	v_writelane_b32 v255, s2, 17
	s_lshl_b32 s2, s66, 8
	s_add_i32 s60, s85, s4
	s_or_b32 s4, s33, 32
	v_writelane_b32 v255, s2, 18
	s_add_i32 s2, s8, 0x18000
	s_mul_i32 s5, s4, 0x90
	v_writelane_b32 v255, s2, 19
	s_add_i32 s2, s7, 0x19000
	s_add_i32 s82, s5, 0
	s_mulk_i32 s4, 0xffb0
	v_writelane_b32 v255, s2, 20
	s_lshl_b32 s72, s66, 2
	s_add_i32 s64, s7, 0x12000
	s_add_i32 s65, s8, 0x11000
	s_lshl_b32 s86, s66, 3
	s_add_i32 s70, s82, s4
	s_mul_i32 s4, s66, 0x600
	v_writelane_b32 v255, s66, 21
	s_lshl_b32 s2, s66, 7
	s_cmp_lt_i32 s6, 2
	v_writelane_b32 v255, s67, 22
	v_writelane_b32 v255, s2, 23
	s_cselect_b64 s[2:3], -1, 0
	v_writelane_b32 v255, s2, 24
	s_ashr_i32 s11, s10, 31
	s_mov_b32 s5, s87
	v_writelane_b32 v255, s3, 25
	v_writelane_b32 v255, s10, 26
	s_mul_i32 s2, s6, 0x5a00
	s_add_i32 s3, s2, 0
	v_writelane_b32 v255, s11, 27
	v_readlane_b32 s8, v253, 20
	s_mul_i32 s2, s6, 0xfffff600
	v_readlane_b32 s10, v253, 22
	v_readlane_b32 s11, v253, 23
	v_readlane_b32 s12, v253, 24
	v_readlane_b32 s13, v253, 25
	v_readlane_b32 s14, v253, 26
	v_readlane_b32 s15, v253, 27
	v_readlane_b32 s16, v253, 28
	v_readlane_b32 s17, v253, 29
	v_writelane_b32 v255, s3, 28
	s_add_i32 s2, s3, s2
	v_readlane_b32 s18, v253, 30
	v_readlane_b32 s19, v253, 31
	v_readlane_b32 s20, v253, 32
	v_readlane_b32 s21, v253, 33
	s_mov_b64 s[10:11], s[14:15]
	s_mov_b64 s[12:13], s[16:17]
	v_writelane_b32 v255, s2, 29
	s_lshl_b32 s2, s6, 2
	s_mov_b64 s[14:15], s[18:19]
	s_add_u32 s98, s14, s0
	s_mov_b64 s[16:17], s[20:21]
	s_addc_u32 s99, s15, s1
	s_lshl_b64 s[6:7], s[86:87], 2
	s_add_u32 s80, s16, s6
	s_addc_u32 s81, s17, s7
	s_add_u32 s62, s12, s0
	s_addc_u32 s63, s13, s1
	s_lshl_b64 s[0:1], s[4:5], 2
	s_add_u32 s0, s10, s0
	v_writelane_b32 v255, s2, 30
	s_addc_u32 s1, s11, s1
	v_writelane_b32 v255, s0, 31
	s_mov_b32 s93, 0
	s_mov_b64 s[68:69], 0
	v_writelane_b32 v255, s1, 32
	s_mov_b64 s[66:67], 0
	v_readlane_b32 s9, v253, 21
	v_readlane_b32 s22, v253, 34
	v_readlane_b32 s23, v253, 35
	s_branch .LBB0_441

; __device__ __forceinline__ void xcd_barrier(const XcdBarrier& b) {
;     asm volatile("s_waitcnt vmcnt(0)" ::: "memory");
;     __syncthreads();
.LBB0_534:
	s_and_b64 vcc, exec, s[0:1]
	s_mov_b32 s93, s4
	s_cbranch_vccz .LBB0_441
	s_getreg_b32 s2, hwreg(HW_REG_XCC_ID, 0, 4)
	v_readfirstlane_b32 s3, v208
	s_nop 3
	s_lshr_b32 s3, s3, 6
	s_cmp_lg_u32 s3, 1
	s_cbranch_scc1 .Lw1_m
	buffer_inv sc1
	s_waitcnt vmcnt(1)
	s_branch .Lw1d_m

; __device__ __forceinline__ unsigned xb_ld(unsigned* p)              { return __hip_atomic_load(p, __ATOMIC_RELAXED, __HIP_MEMORY_SCOPE_AGENT); }
; __device__ __forceinline__ unsigned xb_add(unsigned* p, unsigned v) { return __hip_atomic_fetch_add(p, v, __ATOMIC_RELAXED, __HIP_MEMORY_SCOPE_AGENT); }
; #define XB_SPIN(cond, bar) do { unsigned _sp = 0; while (cond) { __builtin_amdgcn_s_sleep(1); \
;     if ((++_sp & 255u) == 0u) { if (xb_ld(&(bar)[XB_TMO])) break; if (_sp > XB_SPIN_CAP) { atomicAdd(&(bar)[XB_TMO], 1u); break; } } } } while (0)
; __device__ __forceinline__ void xcd_barrier(const XcdBarrier& b) {
;     ...
;     if (threadIdx.x == 0) {
;         unsigned* bar = b.bar;
;         __builtin_amdgcn_s_waitcnt(0);
;         unsigned nloc = b.st[0], nx = b.st[1];
;         if (nloc == 0u) { xcd_barrier_complete(bar, b.x, nloc, nx); b.st[0] = nloc; b.st[1] = nx; }
;         const unsigned old = xb_add(&bar[XB_XSUB(b.x)], 1u);
;         const unsigned gen = old / nloc;
;         if (old + 1u == (gen + 1u) * nloc) {
;             __builtin_amdgcn_fence(__ATOMIC_RELEASE, "agent");
;             asm volatile("s_waitcnt vmcnt(0)" ::: "memory");
;             const unsigned og = xb_add(&bar[XB_TOP], 1u);
;             const unsigned tg = og / nx;
;             if (og + 1u == (tg + 1u) * nx) xb_add(&bar[XB_TOPGEN], 1u);
;             else XB_SPIN(xb_ld(&bar[XB_TOPGEN]) == tg, bar);
;             __builtin_amdgcn_fence(__ATOMIC_ACQUIRE, "agent");
;             xb_add(&bar[XB_XGEN(b.x)], 1u);
;             asm volatile("s_waitcnt vmcnt(0)" ::: "memory");
.Lw1d_m:
	s_barrier
	s_mov_b64 s[0:1], exec
	v_readlane_b32 s4, v253, 2
	v_readlane_b32 s5, v253, 3
	v_readlane_b32 s72, v254, 48
	v_readlane_b32 s80, v254, 50
	v_readlane_b32 s82, v254, 52
	v_readlane_b32 s92, v254, 54
	v_readlane_b32 s94, v254, 56
	v_readlane_b32 s98, v254, 58
	v_readlane_b32 s54, v254, 60
	v_readlane_b32 s56, v254, 62
	v_readlane_b32 s60, v255, 0
	v_readlane_b32 s62, v255, 2
	v_readlane_b32 s22, v255, 21
	s_and_b64 s[4:5], s[0:1], s[4:5]
	v_readlane_b32 s73, v254, 49
	v_readlane_b32 s81, v254, 51
	v_readlane_b32 s83, v254, 53
	v_readlane_b32 s93, v254, 55
	v_readlane_b32 s95, v254, 57
	v_readlane_b32 s99, v254, 59
	v_readlane_b32 s55, v254, 61
	v_readlane_b32 s57, v254, 63
	v_readlane_b32 s61, v255, 1
	v_readlane_b32 s63, v255, 3
	v_readlane_b32 s33, v255, 4
	v_readlane_b32 s85, v255, 5
	v_readlane_b32 s25, v254, 41
	v_readlane_b32 s28, v254, 43
	v_readlane_b32 s23, v255, 22
	s_mov_b64 exec, s[4:5]
	s_cbranch_execz .LBB0_587
	v_mov_b32_e32 v0, 0x20020
	s_waitcnt vmcnt(0) lgkmcnt(0)
	ds_read2_b32 v[2:3], v0 offset1:1
	s_and_b32 s3, s2, 15
	s_lshl_b32 s3, s3, 8
	s_add_u32 s6, s78, 0x1701400
	s_addc_u32 s7, s79, 0
	s_add_u32 s6, s6, s3
	s_addc_u32 s7, s7, 0
	s_add_u32 s10, s78, 0x1703c00
	s_addc_u32 s11, s79, 0
	s_lshr_b32 s3, s3, 1
	s_add_u32 s8, s10, s3
	s_addc_u32 s9, s11, 0
	s_waitcnt lgkmcnt(0)
	v_readfirstlane_b32 s30, v2
	v_readfirstlane_b32 s31, v3
	s_nop 3
	s_cmp_eq_u32 s30, 0
	s_cbranch_scc1 .Lxb_slow_m
	v_readlane_b32 s29, v255, 21
	s_nop 3
	s_lshl_b32 s29, s29, 2
	s_add_i32 s29, s29, 3
	global_atomic_add v2, v173, v212, s[6:7] sc0
	s_add_i32 s32, s29, 1
	s_mul_i32 s5, s32, s30
	s_mul_i32 s32, s32, s31
	s_waitcnt vmcnt(0)
	v_readfirstlane_b32 s3, v2
	s_nop 3
	s_add_i32 s3, s3, 1
	s_cmp_lg_u32 s3, s5
	s_cbranch_scc1 .Lxb_local_m
	buffer_wbl2 sc1
	s_waitcnt vmcnt(0)
	global_atomic_add v173, v212, s[10:11] offset:0
	global_atomic_add v173, v212, s[10:11] offset:128
	global_atomic_add v173, v212, s[10:11] offset:256
	global_atomic_add v173, v212, s[10:11] offset:384
	global_atomic_add v173, v212, s[10:11] offset:512
	global_atomic_add v173, v212, s[10:11] offset:640
	global_atomic_add v173, v212, s[10:11] offset:768
	global_atomic_add v173, v212, s[10:11] offset:896

; #define FRESH_TID() int tid = threadIdx.x; asm volatile("" : "+v"(tid)); const int lane = tid & 63, wave = __builtin_amdgcn_readfirstlane(tid >> 6)
; __device__ __forceinline__ void xcd_barrier(const XcdBarrier& b) {
;     ...
;     }
;     __syncthreads();
; }
; __global__ void __launch_bounds__(512, 2) fwd_megakernel(Args a) {
;     ...
;         {
;             pg8::Gemm g{(const bf16_t*)(a.ws + WS_H), (const bf16_t*)(a.ws + WS_WOUT) + (size_t)l * D * D, MP, D, D}; pg8::StaticOrder S; S.init(MP, D, G, bid);
;             const float* gate = (const float*)(a.ws + WS_MOD) + (size_t)l * NMOD * 3072 + 2048;
;             bf16_t* XB = (bf16_t*)(a.ws + WS_XB);
;             const bf16_t* XBase = (const bf16_t*)(a.ws + (l == 0 ? WS_XB0 : WS_XB));
;             pg8::EpiGate E{nullptr, XBase, a.out, XB, gate, l == 0};
;             const bool small_first = ((bid >> 3) & 1) != 0;
; #pragma unroll 1
;             for (int step = 0; step < 2; ++step) {
;                 if ((step == 0) == small_first) { FRESH_TID();
.LBB0_587:
	s_waitcnt vmcnt(0)
	s_or_b64 exec, exec, s[0:1]
	s_lshl_b64 s[0:1], s[22:23], 21
	v_readlane_b32 s2, v254, 22
	s_add_u32 s2, s2, s0
	v_readlane_b32 s0, v254, 23
	s_addc_u32 s3, s0, s1
	v_readlane_b32 s0, v255, 10
	s_add_u32 s0, s78, s0
	s_addc_u32 s1, s79, 0
	s_add_u32 s4, s0, 0x1202000
	s_addc_u32 s5, s1, 0
	v_readlane_b32 s0, v255, 13
	v_readlane_b32 s1, v255, 14
	s_add_u32 s6, s78, s0
	s_addc_u32 s7, s79, s1
	s_bitcmp1_b32 s22, 0
	s_cselect_b64 s[0:1], -1, 0
	s_xor_b64 s[8:9], s[0:1], -1
	s_add_u32 s10, s6, 0x2000000
	s_addc_u32 s11, s7, 0
	v_readlane_b32 s0, v254, 29
	v_readlane_b32 s1, v254, 30
	s_add_u32 s14, s2, s0
	s_addc_u32 s15, s3, s1
	s_add_u32 s16, s14, 0x40000
	s_addc_u32 s17, s15, 0
	s_add_u32 s18, s14, 0x40080
	s_mov_b64 s[12:13], -1
	s_addc_u32 s19, s15, 0
	s_mov_b32 s0, 0
	s_waitcnt lgkmcnt(0)
	s_barrier
	s_branch .LBB0_590

; #define GRID_BARRIER() do { XcdBarrier xb_; xb_.bar = (unsigned*)(a.ws + WS_BAR); xb_.x = xb_xcc_id(); xb_.st = (volatile LAS unsigned*)(lds + 131072) + 8; xcd_barrier(xb_); } while (0)
; #define FRESH_TID() int tid = threadIdx.x; asm volatile("" : "+v"(tid)); const int lane = tid & 63, wave = __builtin_amdgcn_readfirstlane(tid >> 6)
; __device__ __forceinline__ void xcd_barrier(const XcdBarrier& b) {
;     asm volatile("s_waitcnt vmcnt(0)" ::: "memory");
;     __syncthreads();
; __global__ void __launch_bounds__(512, 2) fwd_megakernel(Args a) {
;     ...
;             for (int step = 0; step < 2; ++step) {
;                 if ((step == 0) == small_first) { FRESH_TID();
;                     for (int t = bid; t < 256; t += G) g2_sample_tile((const bf16_t*)(a.ws + WS_H), (const bf16_t*)(a.ws + WS_WOUT) + (size_t)l * D * D, nullptr, XBase + (size_t)MP * D, a.out + (size_t)MP * D, l == 0 ? XB + (size_t)MP * D : nullptr, gate, lds, t, tid, lane, wave);
;                 } else {
;                     pg8::gemm_phase<pg8::EpiGate, pg8::StaticOrder, true, true>(lds, g, S, E);
;                 }
;             }
;         }
;         if (l == 0) GRID_BARRIER();
.LBB0_683:
	v_readlane_b32 s2, v255, 11
	v_readlane_b32 s3, v255, 12
	s_mov_b64 s[0:1], -1
	s_and_b64 vcc, exec, s[2:3]
	v_readlane_b32 s12, v255, 6
	s_mov_b64 s[26:27], 0x1000
	v_readlane_b32 s13, v255, 7
	s_cbranch_vccz .LBB0_190
	s_getreg_b32 s2, hwreg(HW_REG_XCC_ID, 0, 4)
	v_readfirstlane_b32 s3, v208
	s_nop 3
	s_lshr_b32 s3, s3, 6
	s_cmp_lg_u32 s3, 1
	s_cbranch_scc1 .Lw1_o
	buffer_inv sc1
	s_waitcnt vmcnt(1)
	s_branch .Lw1d_o

; __device__ __forceinline__ unsigned xb_ld(unsigned* p)              { return __hip_atomic_load(p, __ATOMIC_RELAXED, __HIP_MEMORY_SCOPE_AGENT); }
; __device__ __forceinline__ unsigned xb_add(unsigned* p, unsigned v) { return __hip_atomic_fetch_add(p, v, __ATOMIC_RELAXED, __HIP_MEMORY_SCOPE_AGENT); }
; #define XB_SPIN(cond, bar) do { unsigned _sp = 0; while (cond) { __builtin_amdgcn_s_sleep(1); \
;     if ((++_sp & 255u) == 0u) { if (xb_ld(&(bar)[XB_TMO])) break; if (_sp > XB_SPIN_CAP) { atomicAdd(&(bar)[XB_TMO], 1u); break; } } } } while (0)
; __device__ __forceinline__ void xcd_barrier(const XcdBarrier& b) {
;     asm volatile("s_waitcnt vmcnt(0)" ::: "memory");
;     __syncthreads();
;     if (threadIdx.x == 0) {
;         unsigned* bar = b.bar;
;         __builtin_amdgcn_s_waitcnt(0);
;         unsigned nloc = b.st[0], nx = b.st[1];
;         if (nloc == 0u) { xcd_barrier_complete(bar, b.x, nloc, nx); b.st[0] = nloc; b.st[1] = nx; }
;         const unsigned old = xb_add(&bar[XB_XSUB(b.x)], 1u);
;         const unsigned gen = old / nloc;
;         if (old + 1u == (gen + 1u) * nloc) {
;             __builtin_amdgcn_fence(__ATOMIC_RELEASE, "agent");
;             asm volatile("s_waitcnt vmcnt(0)" ::: "memory");
;             const unsigned og = xb_add(&bar[XB_TOP], 1u);
;             const unsigned tg = og / nx;
;             if (og + 1u == (tg + 1u) * nx) xb_add(&bar[XB_TOPGEN], 1u);
;             else XB_SPIN(xb_ld(&bar[XB_TOPGEN]) == tg, bar);
;             __builtin_amdgcn_fence(__ATOMIC_ACQUIRE, "agent");
;             xb_add(&bar[XB_XGEN(b.x)], 1u);
;             asm volatile("s_waitcnt vmcnt(0)" ::: "memory");
.Lw1d_o:
	s_barrier
	s_mov_b64 s[0:1], exec
	v_readlane_b32 s4, v253, 2
	v_readlane_b32 s5, v253, 3
	s_and_b64 s[4:5], s[0:1], s[4:5]
	s_mov_b64 exec, s[4:5]
	s_cbranch_execz .LBB0_189
	v_mov_b32_e32 v0, 0x20020
	s_waitcnt vmcnt(0) lgkmcnt(0)
	ds_read2_b32 v[2:3], v0 offset1:1
	s_and_b32 s3, s2, 15
	s_lshl_b32 s3, s3, 8
	s_add_u32 s6, s78, 0x1701400
	s_addc_u32 s7, s79, 0
	s_add_u32 s6, s6, s3
	s_addc_u32 s7, s7, 0
	s_add_u32 s10, s78, 0x1703c00
	s_addc_u32 s11, s79, 0
	s_lshr_b32 s3, s3, 1
	s_add_u32 s8, s10, s3
	s_addc_u32 s9, s11, 0
	s_waitcnt lgkmcnt(0)
	v_readfirstlane_b32 s30, v2
	v_readfirstlane_b32 s31, v3
	s_nop 3
	s_cmp_eq_u32 s30, 0
	s_cbranch_scc1 .Lxb_slow_o
	s_mov_b32 s29, 4
	global_atomic_add v2, v173, v212, s[6:7] sc0
	s_add_i32 s32, s29, 1
	s_mul_i32 s5, s32, s30
	s_mul_i32 s32, s32, s31
	s_waitcnt vmcnt(0)
	v_readfirstlane_b32 s3, v2
	s_nop 3
	s_add_i32 s3, s3, 1
	s_cmp_lg_u32 s3, s5
	s_cbranch_scc1 .Lxb_local_o
	global_atomic_add v173, v212, s[10:11] offset:0
	global_atomic_add v173, v212, s[10:11] offset:128
	global_atomic_add v173, v212, s[10:11] offset:256
	global_atomic_add v173, v212, s[10:11] offset:384
	global_atomic_add v173, v212, s[10:11] offset:512
	global_atomic_add v173, v212, s[10:11] offset:640
	global_atomic_add v173, v212, s[10:11] offset:768
	global_atomic_add v173, v212, s[10:11] offset:896
